# as previous plus in-proj K-loop phase A: SA10 restage DMAs issued before the ds_reads
# speedup vs baseline: 1.0050x; 1.0022x over previous
; #define PG8_STAGE(bufoff, gbase, voff) do { _Pragma("unroll") for (int _i = 0; _i < 2; ++_i) \
;         __builtin_amdgcn_global_load_lds((const unsigned*)((const char*)(gbase) + (voff)[_i]), (LAS unsigned*)(lds + (bufoff) + ldsw + _i * 8192), 16, 0, 0); } while (0)
; #define PG8_LDA(dst, b, h) do { _Pragma("unroll") for (int m = 0; m < 4; ++m) _Pragma("unroll") for (int k = 0; k < 2; ++k) dst[m][k] = *(const LAS bf16x8*)(lds + PG8_SA(b, h) + aoff + m * 2048 + k * 1024); } while (0)
; #define PG8_LDB(dst, b, h) do { _Pragma("unroll") for (int n = 0; n < 2; ++n) _Pragma("unroll") for (int k = 0; k < 2; ++k) dst[n][k] = *(const LAS bf16x8*)(lds + PG8_SB(b, h) + boff + n * 2048 + k * 1024); } while (0)
; #define PG8_MMA(ai, bj, At, Bt) do { __builtin_amdgcn_s_setprio(1); _Pragma("unroll") for (int m = 0; m < 4; ++m) _Pragma("unroll") for (int n = 0; n < 2; ++n) _Pragma("unroll") for (int k = 0; k < 2; ++k) \
;         acc[ai][bj][m][n] = __builtin_amdgcn_mfma_f32_16x16x32_bf16(Bt[n][k], At[m][k], acc[ai][bj][m][n], 0, 0, 0); __builtin_amdgcn_s_setprio(0); } while (0)
; #define PG8_WAIT_V(n) asm volatile("s_waitcnt vmcnt(" #n ")" ::: "memory")
; #define PG8_WAIT_L(n) asm volatile("s_waitcnt lgkmcnt(" #n ")" ::: "memory")
; #define PG8_BAR __builtin_amdgcn_s_barrier()
; #define PG8_SCHED __builtin_amdgcn_sched_barrier(0)
; template <class Epi, bool ALIGN_EPI = true, class Sched = StaticOrder>
; __device__ __forceinline__ void gemm_phase(LAS unsigned char* lds, const Gemm g, const Sched& S, const Epi& E) {
;     ...
;             const bool last = (t == nt - 2);
;             const char* a1 = cA + (size_t)(t + 1) * kstep;
;             const char* a2 = last ? nA : cA + (size_t)(t + 2) * kstep; const char* b2 = last ? nB : cB + (size_t)(t + 2) * kstep;
;             const char* a3 = a2 + kstep; const char* b3 = b2 + kstep;
;             PG8_LDB(B0, 0, 0); PG8_LDB(B1, 0, 1); PG8_SCHED; PG8_LDA(At, 0, 0); PG8_STAGE(PG8_SA(1, 1), a1 + hstepA, voffA);
;             PG8_WAIT_V(8); PG8_WAIT_L(0); PG8_BAR; PG8_MMA(0, 0, At, B0); PG8_MMA(0, 1, At, B1); PG8_BAR; PG8_SCHED;
.LBB0_374:
	s_add_u32 s36, s58, 0xfffc0080
	s_addc_u32 s37, s59, -1
	s_add_i32 s46, 0, 0x10000
	s_cmp_eq_u32 s45, 12
	s_cselect_b32 s37, s9, s37
	s_cselect_b32 s36, s12, s36
	s_cselect_b32 s61, s7, s44
	s_cselect_b32 s60, s13, s43
	s_add_i32 s48, 0, 0x14000
	s_add_u32 s100, s58, 0xfffc0000
	s_addc_u32 s101, s59, -1
	v_lshl_add_u64 v[196:197], s[100:101], 0, v[136:137]
	s_mov_b32 m0, s38
	v_lshl_add_u64 v[190:191], s[100:101], 0, v[138:139]
	global_load_lds_dwordx4 v[196:197], off
	s_mov_b32 m0, s39
	s_nop 0
	global_load_lds_dwordx4 v[190:191], off
	v_add_u32_e32 v160, s46, v145
	v_add_u32_e32 v176, s48, v145
	ds_read_b128 v[140:143], v160
	ds_read_b128 v[152:155], v160 offset:1024
	ds_read_b128 v[156:159], v160 offset:2048
	ds_read_b128 v[160:163], v160 offset:3072
	ds_read_b128 v[164:167], v176
	ds_read_b128 v[168:171], v176 offset:1024
	ds_read_b128 v[172:175], v176 offset:2048
	ds_read_b128 v[176:179], v176 offset:3072
	v_lshl_add_u64 v[188:189], s[58:59], 0, v[136:137]
	s_add_i32 m0, s11, 0xc000
	ds_read_b128 v[180:183], v151
	ds_read_b128 v[184:187], v151 offset:1024
	ds_read_b128 v[198:201], v151 offset:2048
	ds_read_b128 v[202:205], v151 offset:3072
	ds_read_b128 v[216:219], v151 offset:4096
	ds_read_b128 v[220:223], v151 offset:5120
	ds_read_b128 v[224:227], v151 offset:6144
	ds_read_b128 v[234:237], v151 offset:7168
	global_load_lds_dwordx4 v[188:189], off
	v_lshl_add_u64 v[188:189], s[58:59], 0, v[138:139]
	s_add_i32 m0, s11, 0xe000
	s_nop 0
	global_load_lds_dwordx4 v[188:189], off
	s_cmp_lg_u32 s45, -2
	s_cbranch_scc1 .Lw8_s0p
	s_waitcnt vmcnt(24)
	s_branch .Lwj_s0p
